# domain waits 0/1: L1 invalidate issued with the first poll, second invalidate skipped when the first poll already sees the release; rest as v166
# speedup vs baseline: 1.0043x; 1.0018x over previous
; __device__ __forceinline__ int lane_id() { int l; asm volatile("v_mbcnt_lo_u32_b32 %0, -1, 0\n\tv_mbcnt_hi_u32_b32 %0, -1, %0" : "=v"(l)); return l; }
; __device__ __forceinline__ unsigned pk2(float lo, float hi) { return f2bf(lo) | (f2bf(hi) << 16); }
; __device__ __forceinline__ unsigned xb_ld(unsigned* p)              { return __hip_atomic_load(p, __ATOMIC_RELAXED, __HIP_MEMORY_SCOPE_AGENT); }
; #define XB_SPIN(cond, bar) do { unsigned _sp = 0; while (cond) { __builtin_amdgcn_s_sleep(1); \
;     if ((++_sp & 255u) == 0u) { if (xb_ld(&(bar)[XB_TMO])) break; if (_sp > XB_SPIN_CAP) { atomicAdd(&(bar)[XB_TMO], 1u); break; } } } } while (0)
; __device__ __forceinline__ void xcd_wait(const XcdBarrier& b, unsigned use) {
;     if (b.w0 != 0 && lane_id() == 0) {
;         unsigned* bar = b.bar;
;         XB_SPIN(xb_ld(&bar[XB_TOPGEN]) <= use, bar);
;         __builtin_amdgcn_fence(__ATOMIC_ACQUIRE, "agent");
;         asm volatile("s_waitcnt vmcnt(0)" ::: "memory");
;     }
;     __syncthreads();
; __device__ __forceinline__ void prep_w_half(Frame& F) {
;     ...
;     for (int j = 0; j < 8; ++j) { v2u w; w.x = pk2(pv[j].x, pv[j].y); w.y = pk2(pv[j].z, pv[j].w); pd[64 * j] = w; }
.LBB0_304:
	s_add_u32 s48, s34, 0x2a00000
	s_addc_u32 s49, s35, 0
	s_lshl_b32 s5, s6, 3
	s_add_u32 s5, s48, s5
	s_addc_u32 s6, s49, 0
	s_lshl_b64 s[0:1], s[0:1], 3
	s_add_u32 s0, s5, s0
	s_addc_u32 s1, s6, s1
	v_lshl_add_u64 v[32:33], v[32:33], 3, s[0:1]
	s_waitcnt vmcnt(7)
	v_bfe_u32 v34, v28, 16, 1
	s_movk_i32 s0, 0x7fff
	v_add3_u32 v28, v28, v34, s0
	v_bfe_u32 v34, v29, 16, 1
	v_lshrrev_b32_e32 v28, 16, v28
	v_add3_u32 v29, v29, v34, s0
	s_mov_b32 s1, 0xffff0000
	v_and_or_b32 v28, v29, s1, v28
	v_bfe_u32 v29, v30, 16, 1
	v_add3_u32 v29, v30, v29, s0
	v_bfe_u32 v30, v31, 16, 1
	v_lshrrev_b32_e32 v29, 16, v29
	v_add3_u32 v30, v31, v30, s0
	v_and_or_b32 v29, v30, s1, v29
	global_store_dwordx2 v[32:33], v[28:29], off
	s_waitcnt vmcnt(7)
	v_bfe_u32 v28, v24, 16, 1
	v_add3_u32 v24, v24, v28, s0
	v_bfe_u32 v28, v25, 16, 1
	v_lshrrev_b32_e32 v24, 16, v24
	v_add3_u32 v25, v25, v28, s0
	v_and_or_b32 v24, v25, s1, v24
	v_bfe_u32 v25, v26, 16, 1
	v_add3_u32 v25, v26, v25, s0
	v_bfe_u32 v26, v27, 16, 1
	v_lshrrev_b32_e32 v25, 16, v25
	v_add3_u32 v26, v27, v26, s0
	v_and_or_b32 v25, v26, s1, v25
	global_store_dwordx2 v[32:33], v[24:25], off offset:512
	s_waitcnt vmcnt(7)
	v_bfe_u32 v24, v20, 16, 1
	v_add3_u32 v20, v20, v24, s0
	v_bfe_u32 v24, v21, 16, 1
	v_lshrrev_b32_e32 v20, 16, v20
	v_add3_u32 v21, v21, v24, s0
	v_and_or_b32 v20, v21, s1, v20
	v_bfe_u32 v21, v22, 16, 1
	v_add3_u32 v21, v22, v21, s0
	v_bfe_u32 v22, v23, 16, 1
	v_lshrrev_b32_e32 v21, 16, v21
	v_add3_u32 v22, v23, v22, s0
	v_and_or_b32 v21, v22, s1, v21
	global_store_dwordx2 v[32:33], v[20:21], off offset:1024
	s_waitcnt vmcnt(7)
	v_bfe_u32 v20, v16, 16, 1
	v_add3_u32 v16, v16, v20, s0
	v_bfe_u32 v20, v17, 16, 1
	v_lshrrev_b32_e32 v16, 16, v16
	v_add3_u32 v17, v17, v20, s0
	v_and_or_b32 v16, v17, s1, v16
	v_bfe_u32 v17, v18, 16, 1
	v_add3_u32 v17, v18, v17, s0
	v_bfe_u32 v18, v19, 16, 1
	v_lshrrev_b32_e32 v17, 16, v17
	v_add3_u32 v18, v19, v18, s0
	v_and_or_b32 v17, v18, s1, v17
	global_store_dwordx2 v[32:33], v[16:17], off offset:1536
	s_waitcnt vmcnt(7)
	v_bfe_u32 v16, v12, 16, 1
	v_add3_u32 v12, v12, v16, s0
	v_bfe_u32 v16, v13, 16, 1
	v_lshrrev_b32_e32 v12, 16, v12
	v_add3_u32 v13, v13, v16, s0
	v_and_or_b32 v12, v13, s1, v12
	v_bfe_u32 v13, v14, 16, 1
	v_add3_u32 v13, v14, v13, s0
	v_bfe_u32 v14, v15, 16, 1
	v_lshrrev_b32_e32 v13, 16, v13
	v_add3_u32 v14, v15, v14, s0
	v_and_or_b32 v13, v14, s1, v13
	global_store_dwordx2 v[32:33], v[12:13], off offset:2048
	s_waitcnt vmcnt(7)
	v_bfe_u32 v12, v8, 16, 1
	v_add3_u32 v8, v8, v12, s0
	v_bfe_u32 v12, v9, 16, 1
	v_lshrrev_b32_e32 v8, 16, v8
	v_add3_u32 v9, v9, v12, s0
	v_and_or_b32 v8, v9, s1, v8
	v_bfe_u32 v9, v10, 16, 1
	v_add3_u32 v9, v10, v9, s0
	v_bfe_u32 v10, v11, 16, 1
	v_lshrrev_b32_e32 v9, 16, v9
	v_add3_u32 v10, v11, v10, s0
	v_and_or_b32 v9, v10, s1, v9
	global_store_dwordx2 v[32:33], v[8:9], off offset:2560
	s_waitcnt vmcnt(7)
	v_bfe_u32 v8, v4, 16, 1
	v_add3_u32 v4, v4, v8, s0
	v_bfe_u32 v8, v5, 16, 1
	v_lshrrev_b32_e32 v4, 16, v4
	v_add3_u32 v5, v5, v8, s0
	v_and_or_b32 v4, v5, s1, v4
	v_bfe_u32 v5, v6, 16, 1
	v_add3_u32 v5, v6, v5, s0
	v_bfe_u32 v6, v7, 16, 1
	v_lshrrev_b32_e32 v5, 16, v5
	v_add3_u32 v6, v7, v6, s0
	v_and_or_b32 v5, v6, s1, v5
	global_store_dwordx2 v[32:33], v[4:5], off offset:3072
	s_waitcnt vmcnt(7)
	v_bfe_u32 v4, v0, 16, 1
	v_add3_u32 v0, v0, v4, s0
	v_bfe_u32 v4, v1, 16, 1
	v_lshrrev_b32_e32 v0, 16, v0
	v_add3_u32 v1, v1, v4, s0
	v_and_or_b32 v0, v1, s1, v0
	v_bfe_u32 v1, v2, 16, 1
	v_add3_u32 v1, v2, v1, s0
	v_bfe_u32 v2, v3, 16, 1
	v_lshrrev_b32_e32 v1, 16, v1
	v_add3_u32 v2, v3, v2, s0
	v_and_or_b32 v1, v2, s1, v1
	v_cndmask_b32_e64 v2, 0, 1, s[2:3]
	v_cmp_ne_u32_e64 s[94:95], 1, v2
	s_andn2_b64 vcc, exec, s[2:3]
	global_store_dwordx2 v[32:33], v[0:1], off offset:3584
	s_cbranch_vccnz .LBB0_321
	v_mbcnt_lo_u32_b32 v0, -1, 0
	v_mbcnt_hi_u32_b32 v0, -1, v0
	s_nop 0
	v_cmp_eq_u32_e32 vcc, 0, v0
	s_and_saveexec_b64 s[2:3], vcc
	s_cbranch_execz .LBB0_320
	v_mov_b32_e32 v0, 0x3000
	global_load_dword v0, v0, s[52:53] offset:1280 sc1
	buffer_inv sc1
	s_add_u32 s6, s52, 0x3500
	s_addc_u32 s7, s53, 0
	s_waitcnt vmcnt(0)
	v_cmp_ne_u32_e32 vcc, 0, v0
	s_cbranch_vccnz .LBB0_320
	s_mov_b32 s0, 1
	v_mov_b32_e32 v0, 0
	s_branch .LBB0_309

; __device__ __forceinline__ int lane_id() { int l; asm volatile("v_mbcnt_lo_u32_b32 %0, -1, 0\n\tv_mbcnt_hi_u32_b32 %0, -1, %0" : "=v"(l)); return l; }
; __device__ __forceinline__ unsigned xb_ld(unsigned* p)              { return __hip_atomic_load(p, __ATOMIC_RELAXED, __HIP_MEMORY_SCOPE_AGENT); }
; #define XB_SPIN(cond, bar) do { unsigned _sp = 0; while (cond) { __builtin_amdgcn_s_sleep(1); \
;     if ((++_sp & 255u) == 0u) { if (xb_ld(&(bar)[XB_TMO])) break; if (_sp > XB_SPIN_CAP) { atomicAdd(&(bar)[XB_TMO], 1u); break; } } } } while (0)
; __device__ __forceinline__ void xcd_wait(const XcdBarrier& b, unsigned use) {
;     if (b.w0 != 0 && lane_id() == 0) {
;         unsigned* bar = b.bar;
;         XB_SPIN(xb_ld(&bar[XB_TOPGEN]) <= use, bar);
;         __builtin_amdgcn_fence(__ATOMIC_ACQUIRE, "agent");
;         asm volatile("s_waitcnt vmcnt(0)" ::: "memory");
;     }
;     __syncthreads();
.LBB0_427:
	s_and_b64 vcc, exec, s[94:95]
	s_cbranch_vccnz .LBB0_444
	v_mbcnt_lo_u32_b32 v0, -1, 0
	v_mbcnt_hi_u32_b32 v0, -1, v0
	s_nop 0
	v_cmp_eq_u32_e32 vcc, 0, v0
	s_and_saveexec_b64 s[2:3], vcc
	s_cbranch_execz .LBB0_443
	v_mov_b32_e32 v0, 0x3000
	global_load_dword v0, v0, s[52:53] offset:1280 sc1
	buffer_inv sc1
	s_add_u32 s4, s52, 0x3500
	s_addc_u32 s5, s53, 0
	s_mov_b32 s0, 1
	s_waitcnt vmcnt(0)
	v_cmp_lt_u32_e32 vcc, 1, v0
	s_cbranch_vccnz .LBB0_443
	v_mov_b32_e32 v0, 0
	s_branch .LBB0_432
